# adds: leader's per-XCD generation atomic removed (unused)
# baseline (speedup 1.0000x reference)
.LBB0_178:
	s_or_b64 exec, exec, s[8:9]
	s_mov_b64 s[8:9], exec
	v_mbcnt_lo_u32_b32 v0, s8, 0
	v_mbcnt_hi_u32_b32 v0, s9, v0
	v_cmp_eq_u32_e32 vcc, 0, v0
	s_waitcnt vmcnt(0)
	buffer_inv sc1
	s_and_saveexec_b64 s[16:17], vcc
	s_cbranch_execz .LBB0_180
	s_bcnt1_i32_b64 s3, s[8:9]
	v_mov_b32_e32 v0, 0x2000
	v_mov_b32_e32 v1, s3
.LBB0_180:
	s_or_b64 exec, exec, s[16:17]
	s_waitcnt vmcnt(0)

.LBB0_310:
	s_or_b64 exec, exec, s[8:9]
	s_mov_b64 s[8:9], exec
	v_mbcnt_lo_u32_b32 v0, s8, 0
	v_mbcnt_hi_u32_b32 v0, s9, v0
	v_cmp_eq_u32_e32 vcc, 0, v0
	s_waitcnt vmcnt(0)
	buffer_inv sc1
	s_and_saveexec_b64 s[10:11], vcc
	s_cbranch_execz .LBB0_312
	s_bcnt1_i32_b64 s3, s[8:9]
	v_mov_b32_e32 v0, 0x2000
	v_mov_b32_e32 v1, s3
.LBB0_312:
	s_or_b64 exec, exec, s[10:11]
	s_waitcnt vmcnt(0)

.LBB0_480:
	s_or_b64 exec, exec, s[8:9]
	s_mov_b64 s[8:9], exec
	v_mbcnt_lo_u32_b32 v0, s8, 0
	v_mbcnt_hi_u32_b32 v0, s9, v0
	v_cmp_eq_u32_e32 vcc, 0, v0
	s_waitcnt vmcnt(0)
	buffer_inv sc1
	s_and_saveexec_b64 s[10:11], vcc
	s_cbranch_execz .LBB0_482
	s_bcnt1_i32_b64 s3, s[8:9]
	v_mov_b32_e32 v0, 0x2000
	v_mov_b32_e32 v1, s3
.LBB0_482:
	s_or_b64 exec, exec, s[10:11]
	s_waitcnt vmcnt(0)

.LBB0_561:
	s_or_b64 exec, exec, s[8:9]
	s_mov_b64 s[8:9], exec
	v_mbcnt_lo_u32_b32 v0, s8, 0
	v_mbcnt_hi_u32_b32 v0, s9, v0
	v_cmp_eq_u32_e32 vcc, 0, v0
	s_waitcnt vmcnt(0)
	buffer_inv sc1
	s_and_saveexec_b64 s[10:11], vcc
	s_cbranch_execz .LBB0_563
	s_bcnt1_i32_b64 s3, s[8:9]
	v_mov_b32_e32 v0, 0x2000
	v_mov_b32_e32 v1, s3
.LBB0_563:
	s_or_b64 exec, exec, s[10:11]
	s_waitcnt vmcnt(0)

.LBB0_658:
	s_or_b64 exec, exec, s[6:7]
	s_mov_b64 s[6:7], exec
	v_mbcnt_lo_u32_b32 v0, s6, 0
	v_mbcnt_hi_u32_b32 v0, s7, v0
	v_cmp_eq_u32_e32 vcc, 0, v0
	s_waitcnt vmcnt(0)
	buffer_inv sc1
	s_and_saveexec_b64 s[8:9], vcc
	s_cbranch_execz .LBB0_660
	s_bcnt1_i32_b64 s3, s[6:7]
	v_mov_b32_e32 v0, 0x2000
	v_mov_b32_e32 v1, s3
.LBB0_660:
	s_or_b64 exec, exec, s[8:9]
	s_waitcnt vmcnt(0)

.LBB0_779:
	s_or_b64 exec, exec, s[6:7]
	s_mov_b64 s[6:7], exec
	v_mbcnt_lo_u32_b32 v0, s6, 0
	v_mbcnt_hi_u32_b32 v0, s7, v0
	v_cmp_eq_u32_e32 vcc, 0, v0
	s_waitcnt vmcnt(0)
	buffer_inv sc1
	s_and_saveexec_b64 s[8:9], vcc
	s_cbranch_execz .LBB0_781
	s_bcnt1_i32_b64 s3, s[6:7]
	v_mov_b32_e32 v0, 0x2000
	v_mov_b32_e32 v1, s3
.LBB0_781:
	s_or_b64 exec, exec, s[8:9]
	s_waitcnt vmcnt(0)
